# SEAM5 split-phase: WGs without a split-K piece arrive at G4 entry; pieces on whole handshake quads; P6 on 64 on-time WGs, one row per wave; others exit without waiting
# baseline (speedup 1.0000x reference)
.LBB0_1037:
	s_mov_b32 s98, 0
	s_cmp_lt_i32 s88, 6
	s_cselect_b64 s[6:7], -1, 0
	s_cmp_gt_i32 s88, 5
	s_cselect_b64 s[0:1], -1, 0
	s_cmp_lt_i32 s89, 6
	s_cselect_b64 s[2:3], -1, 0
	s_or_b64 s[0:1], s[0:1], s[2:3]
	s_and_b64 vcc, exec, s[0:1]
	s_cbranch_vccnz .LBB0_1109
	s_movk_i32 s101, 0x1000
	s_cmpk_lg_i32 s96, 0x100
	s_cbranch_scc1 .Lea5_skip
	v_readlane_b32 s99, v249, 0
	s_bfe_u32 s100, s99, 0x30003
	s_lshr_b32 s34, s99, 6
	s_and_b32 s35, s99, 7
	s_lshl_b32 s36, s34, 3
	s_add_u32 s36, s36, s35
	s_cmp_eq_u32 s100, 3
	s_cselect_b32 s101, s36, s101
	s_add_u32 s37, s36, 32
	s_cmp_eq_u32 s100, 4
	s_cselect_b32 s101, s37, s101
	s_cmp_lg_u32 s100, 5
	s_cbranch_scc1 .Lea5_pk
	s_cmp_gt_u32 s35, 5
	s_cbranch_scc1 .Lea5_pk
	s_mul_i32 s36, s34, 6
	s_add_u32 s36, s36, s35
	s_add_u32 s101, s36, 64
.Lea5_pk:
	s_cmpk_lg_i32 s101, 0x1000
	s_cbranch_scc1 .Lea5_skip
	s_waitcnt vmcnt(0) lgkmcnt(0)
	s_barrier
	s_mov_b32 s98, 1
	v_cmp_eq_u32_e32 vcc, 0, v188
	s_and_saveexec_b64 s[34:35], vcc
	s_cbranch_execz .Lea5_done
	v_mov_b32_e32 v2, 0x23fe0
	ds_read_b32 v3, v2
	ds_read_b32 v4, v2 offset:4
	v_readlane_b32 s36, v249, 20
	v_readlane_b32 s50, v249, 18
	v_readlane_b32 s51, v249, 19
	s_lshl_b32 s36, s36, 8
	s_add_u32 s36, s50, s36
	s_addc_u32 s37, s51, 0
	v_mov_b32_e32 v5, 0x1000
	v_mov_b32_e32 v6, 1
	s_nop 1
	global_atomic_add v6, v5, v6, s[36:37] offset:1024 sc0
	s_waitcnt vmcnt(0) lgkmcnt(0)
	v_add_u32_e32 v6, 1, v6
	v_mul_u32_u24_e32 v7, 6, v3
	v_cmp_eq_u32_e32 vcc, v6, v7
	s_and_saveexec_b64 s[52:53], vcc
	s_cbranch_execz .Lea5_done
	buffer_wbl2 sc1
	s_waitcnt vmcnt(0)
	v_mov_b32_e32 v5, 0x313000
	v_mov_b32_e32 v6, 1
	global_atomic_add v6, v5, v6, s[30:31] offset:1024 sc0
	s_waitcnt vmcnt(0)
	v_add_u32_e32 v6, 1, v6
	v_mul_u32_u24_e32 v7, 6, v4
	v_cmp_eq_u32_e32 vcc, v6, v7
	s_and_saveexec_b64 s[54:55], vcc
	s_cbranch_execz .Lea5_done
	v_mov_b32_e32 v5, 0x313500
	v_mov_b32_e32 v6, 1
	global_atomic_add v5, v6, s[30:31]
	s_waitcnt vmcnt(0)

.Lea5_skip:
	v_readlane_b32 s2, v249, 0
	s_cmpk_lt_i32 s2, 0x400
	s_cselect_b64 s[0:1], -1, 0
	s_cmpk_gt_i32 s2, 0x3ff
	v_readfirstlane_b32 s4, v188
	s_cbranch_scc1 .LBB0_1044
	v_readlane_b32 s3, v249, 0
	s_ashr_i32 s2, s3, 31
	s_lshr_b32 s2, s2, 29
	s_add_i32 s9, s3, s2
	s_and_b32 s2, s9, -8
	s_sub_i32 s5, s3, s2
	s_cmp_gt_i32 s5, -1
	s_cbranch_scc0 .LBB0_1041
	s_lshl_b32 s8, s5, 7
	s_ashr_i32 s2, s9, 3
	s_cbranch_execz .LBB0_1042
	s_branch .LBB0_1043

.LBB0_1102:
	v_readlane_b32 s0, v249, 0
	s_cmpk_lg_i32 s96, 0x100
	s_cbranch_scc1 .Lpc_cmp
	s_mov_b32 s0, s101

.LBB0_1109:
	s_cmp_gt_i32 s89, 6
	s_cselect_b64 s[0:1], -1, 0
	s_and_b64 s[2:3], s[6:7], s[0:1]
	s_andn2_b64 vcc, exec, s[2:3]
	s_cbranch_vccnz .LBB0_1159
	s_waitcnt vmcnt(0)
	v_cmp_eq_u32_e32 vcc, 0, v188
	s_waitcnt vmcnt(0) lgkmcnt(0)
	s_barrier
	s_and_saveexec_b64 s[2:3], vcc
	s_cbranch_execz .LBB0_1158
	s_cmp_lg_u32 s98, 1
	s_cbranch_scc1 .Lea5_normal
	v_readlane_b32 s99, v249, 0
	s_bfe_u32 s100, s99, 0x30003
	s_cmp_lt_u32 s100, 6
	s_cbranch_scc1 .LBB0_1158
	v_mov_b32_e32 v0, 0x313500
.Lea5_wait:
	global_load_dword v1, v0, s[30:31] sc1
	s_waitcnt vmcnt(0)
	v_cmp_ne_u32_e32 vcc, 5, v1
	s_cbranch_vccnz .Lea5_waited
	s_sleep 1
	s_branch .Lea5_wait

.Lea5_normal:
	s_add_i32 s4, 0, 0x23fe0
	v_mov_b32_e32 v0, s4
	s_waitcnt vmcnt(0) expcnt(0) lgkmcnt(0)
	ds_read_b32 v2, v0
	s_add_i32 s4, 0, 0x23fe4
	v_mov_b32_e32 v0, s4
	ds_read_b32 v0, v0
	s_waitcnt lgkmcnt(1)
	v_cmp_ne_u32_e32 vcc, 0, v2
	s_cbranch_vccnz .LBB0_1126
	v_readlane_b32 s4, v249, 17
	s_mul_i32 s24, s97, s4
	s_add_u32 s4, s30, 0x310200
	s_addc_u32 s5, s31, 0
	s_add_u32 s6, s30, 0x310400
	s_addc_u32 s7, s31, 0
	s_add_u32 s8, s30, 0x310500
	s_addc_u32 s9, s31, 0
	s_add_u32 s10, s30, 0x310600
	s_addc_u32 s11, s31, 0
	s_add_u32 s12, s30, 0x310700
	s_addc_u32 s13, s31, 0
	s_add_u32 s14, s30, 0x310800
	s_addc_u32 s15, s31, 0
	s_add_u32 s16, s30, 0x310900
	s_addc_u32 s17, s31, 0
	s_add_u32 s18, s30, 0x310a00
	s_addc_u32 s19, s31, 0
	s_add_u32 s20, s30, 0x310b00
	s_addc_u32 s21, s31, 0
	s_add_u32 s22, s30, 0x310c00
	s_addc_u32 s23, s31, 0
	s_add_u32 s34, s30, 0x310d00
	s_addc_u32 s35, s31, 0
	s_add_u32 s36, s30, 0x310e00
	s_addc_u32 s37, s31, 0
	s_add_u32 s38, s30, 0x310f00
	s_addc_u32 s39, s31, 0
	s_add_u32 s40, s30, 0x311000
	s_addc_u32 s41, s31, 0
	s_add_u32 s42, s30, 0x311100
	s_addc_u32 s43, s31, 0
	s_add_u32 s44, s30, 0x311200
	s_addc_u32 s45, s31, 0
	s_add_u32 s46, s30, 0x311300
	s_mul_i32 s24, s24, s96
	s_addc_u32 s47, s31, 0
	s_mov_b32 s25, 1
	v_mov_b32_e32 v16, 0
	s_branch .LBB0_1114

.Lp6_new:
	s_lshr_b32 s3, s0, 3
	s_bfe_u32 s1, s3, 0x30003
	s_sub_u32 s1, s1, 6
	s_cmp_gt_u32 s1, 1
	s_cbranch_scc1 .Lp6_none
	s_lshl_b32 s1, s1, 2
	s_lshr_b32 s4, s3, 6
	s_add_u32 s1, s1, s4
	s_lshl_b32 s1, s1, 3
	s_and_b32 s3, s3, 7
	s_add_u32 s1, s1, s3
	s_lshl_b32 s3, s1, 3
	v_add_u32_e32 v16, s3, v22
	s_branch .Lp6_m
.Lp6_none:
	v_mov_b32_e32 v16, 0x10000
